# loop v3: merged lgkmcnt waits (one per fragment group) on top of spread LDS reads + conflict-free K swizzle
# speedup vs baseline: 1.0168x; 1.0086x over previous
; #define LAS __attribute__((address_space(3)))
; __device__ __forceinline__ int v_rd_base(int lane) { return ((lane & 3) << 3) | (((lane >> 2) & 3) << 6) | (((lane >> 4) & 1) << 5) | (((lane >> 5) & 1) << 8); }
; template <bool SAFE>
; __device__ __forceinline__ bool attn_unit_prompt_t(LAS unsigned char* lds, const bf16* Kg, const bf16* Vg, const bf16* Qrow0, bf16* Orow0, int NT, int qpos0, int h, const float* gnorm) {
;     ...
;   const LAS char* vrd = V_lds + v_rd_base(lane);
.Lmy533:
	s_mov_b32 s37, s64
	s_add_i32 s32, s37, 0
	s_waitcnt vmcnt(4)
	s_barrier
	v_add_u32_e32 v161, s32, v9
	v_add_u32_e32 v211, s32, v10
	ds_read_b128 v[4:7], v161
	ds_read_b128 v[14:17], v161 offset:8192
	s_mov_b32 s64, s8
	s_and_b32 s66, s36, 0xc000
	v_add_u32_e32 v147, s66, v194
	s_add_i32 s67, s36, 0x4000
	s_and_b32 s67, s67, 0xc000
	v_add_u32_e32 v160, s67, v194
	s_waitcnt lgkmcnt(10)
	v_mfma_f32_32x32x16_bf16 v[66:81], v[130:133], v[246:249], v[66:81]
	v_exp_f32_e32 v98, v98
	ds_read_b64_tr_b16 v[246:247], v147 offset:57344
	ds_read_b64_tr_b16 v[248:249], v147 offset:59392
	ds_read_b128 v[148:151], v211
	v_mfma_f32_32x32x16_bf16 v[50:65], v[130:133], v[250:253], v[50:65]
	v_exp_f32_e32 v99, v99
	ds_read_b64_tr_b16 v[250:251], v147 offset:57856
	ds_read_b64_tr_b16 v[252:253], v147 offset:59904
	ds_read_b128 v[152:155], v211 offset:8192
	v_mfma_f32_32x32x16_bf16 v[34:49], v[130:133], v[198:201], v[34:49]
	v_exp_f32_e32 v100, v100
	ds_read_b64_tr_b16 v[198:199], v147 offset:58368
	ds_read_b64_tr_b16 v[200:201], v147 offset:60416
	v_add_u32_e32 v161, s32, v11
	v_add_u32_e32 v211, s32, v12
	v_mfma_f32_32x32x16_bf16 v[18:33], v[130:133], v[202:205], v[18:33]
	v_exp_f32_e32 v101, v101
	v_exp_f32_e32 v102, v102
	ds_read_b64_tr_b16 v[202:203], v147 offset:58880
	ds_read_b64_tr_b16 v[204:205], v147 offset:60928
	v_mfma_f32_16x16x32_bf16 v[182:185], v[130:133], v[162:165], v[182:185]
	ds_read_b128 v[156:159], v161
	ds_read_b128 v[186:189], v161 offset:8192
	s_waitcnt lgkmcnt(14)
	v_mfma_f32_32x32x16_bf16 v[66:81], v[134:137], v[206:209], v[66:81]
	v_exp_f32_e32 v103, v103
	ds_read_b64_tr_b16 v[206:207], v147 offset:61440
	ds_read_b64_tr_b16 v[208:209], v147 offset:63488
	ds_read_b128 v[224:227], v211
	v_mfma_f32_32x32x16_bf16 v[50:65], v[134:137], v[236:239], v[50:65]
	v_exp_f32_e32 v104, v104
	ds_read_b64_tr_b16 v[236:237], v147 offset:61952
	ds_read_b64_tr_b16 v[238:239], v147 offset:64000
	ds_read_b128 v[228:231], v211 offset:8192
	v_mfma_f32_32x32x16_bf16 v[34:49], v[134:137], v[240:243], v[34:49]
	v_exp_f32_e32 v105, v105
	v_exp_f32_e32 v106, v106
	ds_read_b64_tr_b16 v[240:241], v147 offset:62464
	ds_read_b64_tr_b16 v[242:243], v147 offset:64512
	v_mfma_f32_32x32x16_bf16 v[18:33], v[134:137], v[232:235], v[18:33]
	v_exp_f32_e32 v107, v107
	v_exp_f32_e32 v108, v108
	ds_read_b64_tr_b16 v[232:233], v147 offset:62976
	ds_read_b64_tr_b16 v[234:235], v147 offset:65024
	v_mfma_f32_16x16x32_bf16 v[182:185], v[134:137], v[162:165], v[182:185]
	s_add_u32 s48, s0, s12
	s_addc_u32 s54, s1, s13
	s_add_u32 s8, s48, 0x138000
	s_addc_u32 s9, s54, 0
	s_add_i32 s15, s64, s30
	s_add_u32 s55, s21, s12
	s_addc_u32 s93, s34, s13
	s_mov_b32 m0, s15
	s_nop 0
	global_load_lds_dwordx4 v214, s[8:9] offset:0
	global_load_lds_dwordx4 v215, s[8:9] offset:1024
	s_waitcnt lgkmcnt(14)
	v_mfma_f32_32x32x16_bf16 v[130:145], v[4:7], v[178:181], v[82:97]
	s_add_u32 s8, s55, 0xcf39200
	s_addc_u32 s9, s93, 0
	s_add_i32 s15, s36, 0xffffc000
	s_and_b32 s15, s15, 0xc000
	s_add_i32 s15, s15, s31
	s_mov_b32 m0, s15
	s_nop 0
	global_load_lds_dwordx4 v216, s[8:9] offset:0
	global_load_lds_dwordx4 v217, s[8:9] offset:1024
	v_mfma_f32_32x32x16_bf16 v[130:145], v[148:151], v[174:177], v[130:145]
	v_exp_f32_e32 v109, v109
	v_exp_f32_e32 v110, v110
	s_waitcnt lgkmcnt(4)
	v_mfma_f32_32x32x16_bf16 v[130:145], v[156:159], v[170:173], v[130:145]
	v_exp_f32_e32 v111, v111
	v_exp_f32_e32 v112, v112
	v_mfma_f32_32x32x16_bf16 v[130:145], v[224:227], v[166:169], v[130:145]
	v_exp_f32_e32 v113, v113
	v_mfma_f32_32x32x16_bf16 v[114:129], v[14:17], v[178:181], v[82:97]
	v_cvt_pk_bf16_f32 v98, v98, v99
	v_cvt_pk_bf16_f32 v99, v100, v101
	v_mfma_f32_32x32x16_bf16 v[114:129], v[152:155], v[174:177], v[114:129]
	v_cvt_pk_bf16_f32 v100, v102, v103
	v_cvt_pk_bf16_f32 v101, v104, v105
	v_mfma_f32_32x32x16_bf16 v[114:129], v[186:189], v[170:173], v[114:129]
	v_cvt_pk_bf16_f32 v102, v106, v107
	v_cvt_pk_bf16_f32 v103, v108, v109
	v_mfma_f32_32x32x16_bf16 v[114:129], v[228:231], v[166:169], v[114:129]
	v_cvt_pk_bf16_f32 v104, v110, v111
	v_cvt_pk_bf16_f32 v105, v112, v113
	s_waitcnt lgkmcnt(12)
	v_mfma_f32_32x32x16_bf16 v[66:81], v[98:101], v[246:249], v[66:81]
	v_exp_f32_e32 v130, v130
	v_exp_f32_e32 v131, v131
	ds_read_b64_tr_b16 v[246:247], v160 offset:49152
	ds_read_b64_tr_b16 v[248:249], v160 offset:51200
	v_mfma_f32_32x32x16_bf16 v[50:65], v[98:101], v[250:253], v[50:65]
	v_exp_f32_e32 v132, v132
	v_exp_f32_e32 v133, v133
	ds_read_b64_tr_b16 v[250:251], v160 offset:49664
	ds_read_b64_tr_b16 v[252:253], v160 offset:51712
	v_mfma_f32_32x32x16_bf16 v[34:49], v[98:101], v[198:201], v[34:49]
	v_exp_f32_e32 v134, v134
	v_exp_f32_e32 v135, v135
	ds_read_b64_tr_b16 v[198:199], v160 offset:50176
	ds_read_b64_tr_b16 v[200:201], v160 offset:52224
	v_mfma_f32_32x32x16_bf16 v[18:33], v[98:101], v[202:205], v[18:33]
	v_exp_f32_e32 v136, v136
	v_exp_f32_e32 v137, v137
	ds_read_b64_tr_b16 v[202:203], v160 offset:50688
	ds_read_b64_tr_b16 v[204:205], v160 offset:52736
	v_mfma_f32_16x16x32_bf16 v[182:185], v[98:101], v[162:165], v[182:185]
	v_exp_f32_e32 v138, v138
	v_exp_f32_e32 v139, v139
	s_waitcnt lgkmcnt(8)
	v_mfma_f32_32x32x16_bf16 v[66:81], v[102:105], v[206:209], v[66:81]
	v_exp_f32_e32 v140, v140
	v_exp_f32_e32 v141, v141
	ds_read_b64_tr_b16 v[206:207], v160 offset:53248
	ds_read_b64_tr_b16 v[208:209], v160 offset:55296
	v_mfma_f32_32x32x16_bf16 v[50:65], v[102:105], v[236:239], v[50:65]
	v_exp_f32_e32 v142, v142
	v_exp_f32_e32 v143, v143
	ds_read_b64_tr_b16 v[236:237], v160 offset:53760
	ds_read_b64_tr_b16 v[238:239], v160 offset:55808
	v_mfma_f32_32x32x16_bf16 v[34:49], v[102:105], v[240:243], v[34:49]
	v_exp_f32_e32 v144, v144
	v_exp_f32_e32 v145, v145
	ds_read_b64_tr_b16 v[240:241], v160 offset:54272
	ds_read_b64_tr_b16 v[242:243], v160 offset:56320
	v_mfma_f32_32x32x16_bf16 v[18:33], v[102:105], v[232:235], v[18:33]
	v_cvt_pk_bf16_f32 v130, v130, v131
	v_cvt_pk_bf16_f32 v131, v132, v133
	v_cvt_pk_bf16_f32 v132, v134, v135
	v_cvt_pk_bf16_f32 v133, v136, v137
	ds_read_b64_tr_b16 v[232:233], v160 offset:54784
	ds_read_b64_tr_b16 v[234:235], v160 offset:56832
	v_mfma_f32_16x16x32_bf16 v[182:185], v[102:105], v[162:165], v[182:185]
	v_cvt_pk_bf16_f32 v134, v138, v139
	v_cvt_pk_bf16_f32 v135, v140, v141
	v_cvt_pk_bf16_f32 v136, v142, v143
	v_cvt_pk_bf16_f32 v137, v144, v145
	s_add_i32 s32, s65, 0
	s_waitcnt vmcnt(4)
	s_barrier
; #define LAS __attribute__((address_space(3)))
; __device__ __forceinline__ int v_rd_base(int lane) { return ((lane & 3) << 3) | (((lane >> 2) & 3) << 6) | (((lane >> 4) & 1) << 5) | (((lane >> 5) & 1) << 8); }
; template <bool SAFE>
; __device__ __forceinline__ bool attn_unit_prompt_t(LAS unsigned char* lds, const bf16* Kg, const bf16* Vg, const bf16* Qrow0, bf16* Orow0, int NT, int qpos0, int h, const float* gnorm) {
;     ...
;   const LAS char* vrd = V_lds + v_rd_base(lane);
	v_add_u32_e32 v161, s32, v9
	v_add_u32_e32 v211, s32, v10
	ds_read_b128 v[4:7], v161
	ds_read_b128 v[14:17], v161 offset:8192
	s_add_i32 s67, s36, 0x8000
	s_and_b32 s67, s67, 0xc000
	v_add_u32_e32 v147, s67, v194
	s_waitcnt lgkmcnt(10)
	v_mfma_f32_32x32x16_bf16 v[66:81], v[130:133], v[246:249], v[66:81]
	v_exp_f32_e32 v114, v114
	ds_read_b64_tr_b16 v[246:247], v160 offset:57344
	ds_read_b64_tr_b16 v[248:249], v160 offset:59392
	ds_read_b128 v[148:151], v211
	v_mfma_f32_32x32x16_bf16 v[50:65], v[130:133], v[250:253], v[50:65]
	v_exp_f32_e32 v115, v115
	ds_read_b64_tr_b16 v[250:251], v160 offset:57856
	ds_read_b64_tr_b16 v[252:253], v160 offset:59904
	ds_read_b128 v[152:155], v211 offset:8192
	v_mfma_f32_32x32x16_bf16 v[34:49], v[130:133], v[198:201], v[34:49]
	v_exp_f32_e32 v116, v116
	ds_read_b64_tr_b16 v[198:199], v160 offset:58368
	ds_read_b64_tr_b16 v[200:201], v160 offset:60416
	v_add_u32_e32 v161, s32, v11
	v_add_u32_e32 v211, s32, v12
	v_mfma_f32_32x32x16_bf16 v[18:33], v[130:133], v[202:205], v[18:33]
	v_exp_f32_e32 v117, v117
	v_exp_f32_e32 v118, v118
	ds_read_b64_tr_b16 v[202:203], v160 offset:58880
	ds_read_b64_tr_b16 v[204:205], v160 offset:60928
	v_mfma_f32_16x16x32_bf16 v[182:185], v[130:133], v[162:165], v[182:185]
	ds_read_b128 v[156:159], v161
	ds_read_b128 v[186:189], v161 offset:8192
	s_waitcnt lgkmcnt(14)
	v_mfma_f32_32x32x16_bf16 v[66:81], v[134:137], v[206:209], v[66:81]
	v_exp_f32_e32 v119, v119
	ds_read_b64_tr_b16 v[206:207], v160 offset:61440
	ds_read_b64_tr_b16 v[208:209], v160 offset:63488
	ds_read_b128 v[224:227], v211
	v_mfma_f32_32x32x16_bf16 v[50:65], v[134:137], v[236:239], v[50:65]
	v_exp_f32_e32 v120, v120
	ds_read_b64_tr_b16 v[236:237], v160 offset:61952
	ds_read_b64_tr_b16 v[238:239], v160 offset:64000
	ds_read_b128 v[228:231], v211 offset:8192
	v_mfma_f32_32x32x16_bf16 v[34:49], v[134:137], v[240:243], v[34:49]
	v_exp_f32_e32 v121, v121
	v_exp_f32_e32 v122, v122
	ds_read_b64_tr_b16 v[240:241], v160 offset:62464
	ds_read_b64_tr_b16 v[242:243], v160 offset:64512
	v_mfma_f32_32x32x16_bf16 v[18:33], v[134:137], v[232:235], v[18:33]
	v_exp_f32_e32 v123, v123
	v_exp_f32_e32 v124, v124
	ds_read_b64_tr_b16 v[232:233], v160 offset:62976
	ds_read_b64_tr_b16 v[234:235], v160 offset:65024
	v_mfma_f32_16x16x32_bf16 v[182:185], v[134:137], v[162:165], v[182:185]
	s_add_u32 s14, s48, 0x1a0000
	s_addc_u32 s15, s54, 0
	s_add_i32 s48, s37, s30
	s_mov_b32 m0, s48
	s_nop 0
	global_load_lds_dwordx4 v214, s[14:15] offset:0
	global_load_lds_dwordx4 v215, s[14:15] offset:1024
	s_waitcnt lgkmcnt(14)
	v_mfma_f32_32x32x16_bf16 v[130:145], v[4:7], v[178:181], v[82:97]
	s_add_u32 s14, s55, 0xcfa1200
	s_addc_u32 s15, s93, 0
	s_add_i32 s48, s66, s31
	s_mov_b32 m0, s48
	s_nop 0
	global_load_lds_dwordx4 v216, s[14:15] offset:0
	global_load_lds_dwordx4 v217, s[14:15] offset:1024
	v_mfma_f32_32x32x16_bf16 v[130:145], v[148:151], v[174:177], v[130:145]
	v_exp_f32_e32 v125, v125
	v_exp_f32_e32 v126, v126
	s_waitcnt lgkmcnt(4)
	v_mfma_f32_32x32x16_bf16 v[130:145], v[156:159], v[170:173], v[130:145]
	v_exp_f32_e32 v127, v127
	v_exp_f32_e32 v128, v128
	v_mfma_f32_32x32x16_bf16 v[130:145], v[224:227], v[166:169], v[130:145]
	v_exp_f32_e32 v129, v129
	v_mfma_f32_32x32x16_bf16 v[98:113], v[14:17], v[178:181], v[82:97]
	v_cvt_pk_bf16_f32 v114, v114, v115
	v_cvt_pk_bf16_f32 v115, v116, v117
	v_mfma_f32_32x32x16_bf16 v[98:113], v[152:155], v[174:177], v[98:113]
	v_cvt_pk_bf16_f32 v116, v118, v119
	v_cvt_pk_bf16_f32 v117, v120, v121
	v_mfma_f32_32x32x16_bf16 v[98:113], v[186:189], v[170:173], v[98:113]
	v_cvt_pk_bf16_f32 v118, v122, v123
	v_cvt_pk_bf16_f32 v119, v124, v125
	v_mfma_f32_32x32x16_bf16 v[98:113], v[228:231], v[166:169], v[98:113]
	v_cvt_pk_bf16_f32 v120, v126, v127
	v_cvt_pk_bf16_f32 v121, v128, v129
	s_waitcnt lgkmcnt(12)
	v_mfma_f32_32x32x16_bf16 v[66:81], v[114:117], v[246:249], v[66:81]
	v_exp_f32_e32 v130, v130
	v_exp_f32_e32 v131, v131
	ds_read_b64_tr_b16 v[246:247], v147 offset:49152
	ds_read_b64_tr_b16 v[248:249], v147 offset:51200
	v_mfma_f32_32x32x16_bf16 v[50:65], v[114:117], v[250:253], v[50:65]
	v_exp_f32_e32 v132, v132
	v_exp_f32_e32 v133, v133
	ds_read_b64_tr_b16 v[250:251], v147 offset:49664
	ds_read_b64_tr_b16 v[252:253], v147 offset:51712
	v_mfma_f32_32x32x16_bf16 v[34:49], v[114:117], v[198:201], v[34:49]
	v_exp_f32_e32 v134, v134
	v_exp_f32_e32 v135, v135
	ds_read_b64_tr_b16 v[198:199], v147 offset:50176
	ds_read_b64_tr_b16 v[200:201], v147 offset:52224
	v_mfma_f32_32x32x16_bf16 v[18:33], v[114:117], v[202:205], v[18:33]
	v_exp_f32_e32 v136, v136
	v_exp_f32_e32 v137, v137
	ds_read_b64_tr_b16 v[202:203], v147 offset:50688
	ds_read_b64_tr_b16 v[204:205], v147 offset:52736
	v_mfma_f32_16x16x32_bf16 v[182:185], v[114:117], v[162:165], v[182:185]
	v_exp_f32_e32 v138, v138
	v_exp_f32_e32 v139, v139
	s_waitcnt lgkmcnt(8)
	v_mfma_f32_32x32x16_bf16 v[66:81], v[118:121], v[206:209], v[66:81]
	v_exp_f32_e32 v140, v140
	v_exp_f32_e32 v141, v141
	ds_read_b64_tr_b16 v[206:207], v147 offset:53248
	ds_read_b64_tr_b16 v[208:209], v147 offset:55296
	v_mfma_f32_32x32x16_bf16 v[50:65], v[118:121], v[236:239], v[50:65]
	v_exp_f32_e32 v142, v142
	v_exp_f32_e32 v143, v143
	ds_read_b64_tr_b16 v[236:237], v147 offset:53760
	ds_read_b64_tr_b16 v[238:239], v147 offset:55808
	v_mfma_f32_32x32x16_bf16 v[34:49], v[118:121], v[240:243], v[34:49]
	v_exp_f32_e32 v144, v144
	v_exp_f32_e32 v145, v145
	ds_read_b64_tr_b16 v[240:241], v147 offset:54272
	ds_read_b64_tr_b16 v[242:243], v147 offset:56320
	v_mfma_f32_32x32x16_bf16 v[18:33], v[118:121], v[232:235], v[18:33]
	v_cvt_pk_bf16_f32 v130, v130, v131
	v_cvt_pk_bf16_f32 v131, v132, v133
	v_cvt_pk_bf16_f32 v132, v134, v135
	v_cvt_pk_bf16_f32 v133, v136, v137
	ds_read_b64_tr_b16 v[232:233], v147 offset:54784
	ds_read_b64_tr_b16 v[234:235], v147 offset:56832
	v_mfma_f32_16x16x32_bf16 v[182:185], v[118:121], v[162:165], v[182:185]
	v_cvt_pk_bf16_f32 v134, v138, v139
	v_cvt_pk_bf16_f32 v135, v140, v141
	v_cvt_pk_bf16_f32 v136, v142, v143
	v_cvt_pk_bf16_f32 v137, v144, v145
	s_add_i32 s35, s35, 2
	s_add_i32 s36, s36, 0x8000
	s_add_u32 s12, s12, 0xd0000
	s_addc_u32 s13, s13, 0
	s_cmp_ge_i32 s35, s20
	s_cbranch_scc1 .Lmy533_exit
	s_mov_b32 s8, s65
	s_mov_b32 s65, s37
	s_branch .Lmy533
